# G1 epilogue: lane transpose (ds_bpermute of data+address) so adjacent lanes store contiguous 64B row pieces; global_store instead of flat_store
# speedup vs baseline: 1.0029x; 1.0005x over previous
; #define PG8_STAGE(bufoff, gbase, voff) do { _Pragma("unroll") for (int _i = 0; _i < 2; ++_i) \
;         __builtin_amdgcn_global_load_lds((const unsigned*)((const char*)(gbase) + (voff)[_i]), (PG8_LAS unsigned*)(lds + (bufoff) + ldsw + _i * 8192), 16, 0, 0); } while (0)
; #define PG8_LDA(dst, b, h) do { _Pragma("unroll") for (int m = 0; m < 4; ++m) _Pragma("unroll") for (int k = 0; k < 2; ++k) dst[m][k] = *(const PG8_LAS bf16x8*)(lds + PG8_SA(b, h) + aoff + m * 2048 + k * 1024); } while (0)
; #define PG8_LDB(dst, b, h) do { _Pragma("unroll") for (int n = 0; n < 2; ++n) _Pragma("unroll") for (int k = 0; k < 2; ++k) dst[n][k] = *(const PG8_LAS bf16x8*)(lds + PG8_SB(b, h) + boff + n * 2048 + k * 1024); } while (0)
; #define PG8_MMA(ai, bj, At, Bt) do { __builtin_amdgcn_s_setprio(1); _Pragma("unroll") for (int m = 0; m < 4; ++m) _Pragma("unroll") for (int n = 0; n < 2; ++n) _Pragma("unroll") for (int k = 0; k < 2; ++k) \
;         acc[ai][bj][m][n] = __builtin_amdgcn_mfma_f32_16x16x32_bf16(Bt[n][k], At[m][k], acc[ai][bj][m][n], 0, 0, 0); __builtin_amdgcn_s_setprio(0); } while (0)
; #define PG8_WAIT_V(n) asm volatile("s_waitcnt vmcnt(" #n ")" ::: "memory")
; template <class Epi, class Sched, bool ALIGN_EPI = false, bool SP2 = false>
; __device__ __forceinline__ void gemm_phase(PG8_LAS unsigned char* lds, const Gemm g, const Sched& S, const Epi& E) {
;     ...
;             const bool last = (t == nt - 2);
;             const char* a1 = cA + (size_t)(t + 1) * kstep;
;             const char* a2 = last ? nA : cA + (size_t)(t + 2) * kstep; const char* b2 = last ? nB : cB + (size_t)(t + 2) * kstep;
;             const char* a3 = a2 + kstep; const char* b3 = b2 + kstep;
;             if (last && has_next) S.a_ready(nxt);
;             if constexpr (Epi::MID) { if (t == nt / 2) E.mid(acc, cur, wr, wc, fr, fq); }
;             if constexpr (SP2) {
;             PG8_LDB(B0, 0, 0); PG8_LDB(B1, 0, 1); PG8_SCHED; PG8_LDA(At, 0, 0); PG8_STAGE(PG8_SA(1, 1), a1 + hstep, voffA);
;             PG8_WAIT_V(8); PG8_WAIT_L(0); PG8_BAR; PG8_MMA(0, 0, At, B0); PG8_MMA(0, 1, At, B1); PG8_BAR; PG8_SCHED;
;             PG8_LDA(At, 0, 1); PG8_STAGE(PG8_SB(0, 0), b2, voffB); PG8_STAGE(PG8_SB(0, 1), b2 + hstep, voffB); PG8_STAGE(PG8_SA(0, 0), a2, voffA);
;             PG8_WAIT_V(8); PG8_WAIT_L(0); PG8_BAR; PG8_MMA(1, 0, At, B0); PG8_MMA(1, 1, At, B1); PG8_BAR; PG8_SCHED;
.LBB0_418:
	s_add_u32 s56, s40, 0xfff80080
	s_addc_u32 s57, s41, -1
	s_add_i32 s75, 0, 0x10000
	s_cmp_eq_u32 s74, 28
	s_cselect_b32 s59, s2, s57
	s_cselect_b32 s58, s3, s56
	v_add_u32_e32 v142, s75, v156
	s_cselect_b32 s57, s49, s73
	s_cselect_b32 s56, s51, s72
	s_add_i32 s78, 0, 0x14000
	ds_read_b128 v[152:155], v142
	ds_read_b128 v[160:163], v142 offset:1024
	ds_read_b128 v[164:167], v142 offset:2048
	ds_read_b128 v[182:185], v142 offset:3072
	v_add_u32_e32 v142, s78, v156
	ds_read_b128 v[186:189], v142
	ds_read_b128 v[190:193], v142 offset:1024
	ds_read_b128 v[194:197], v142 offset:2048
	ds_read_b128 v[198:201], v142 offset:3072
	v_lshl_add_u64 v[168:169], s[40:41], 0, v[150:151]
	s_add_i32 m0, s63, 0xc000
	ds_read_b128 v[202:205], v158
	ds_read_b128 v[206:209], v158 offset:1024
	ds_read_b128 v[214:217], v158 offset:2048
	ds_read_b128 v[218:221], v158 offset:3072
	ds_read_b128 v[222:225], v158 offset:4096
	ds_read_b128 v[226:229], v158 offset:5120
	ds_read_b128 v[230:233], v158 offset:6144
	ds_read_b128 v[234:237], v158 offset:7168
	global_load_lds_dwordx4 v[168:169], off
	v_lshl_add_u64 v[168:169], s[40:41], 0, v[136:137]
	s_add_i32 m0, s63, 0xe000
	s_nop 0
	global_load_lds_dwordx4 v[168:169], off
	s_waitcnt vmcnt(8)
	s_waitcnt lgkmcnt(0)
	s_setprio 1
	s_barrier
	v_mfma_f32_16x16x32_bf16 v[126:129], v[152:155], v[202:205], v[126:129]
	v_mfma_f32_16x16x32_bf16 v[122:125], v[164:167], v[202:205], v[122:125]
	v_mfma_f32_16x16x32_bf16 v[110:113], v[152:155], v[214:217], v[110:113]
	v_mfma_f32_16x16x32_bf16 v[106:109], v[164:167], v[214:217], v[106:109]
	v_mfma_f32_16x16x32_bf16 v[94:97], v[152:155], v[222:225], v[94:97]
	v_mfma_f32_16x16x32_bf16 v[90:93], v[164:167], v[222:225], v[90:93]
	v_mfma_f32_16x16x32_bf16 v[78:81], v[152:155], v[230:233], v[78:81]
	v_mfma_f32_16x16x32_bf16 v[74:77], v[164:167], v[230:233], v[74:77]
	v_mfma_f32_16x16x32_bf16 v[126:129], v[160:163], v[206:209], v[126:129]
	v_mfma_f32_16x16x32_bf16 v[122:125], v[182:185], v[206:209], v[122:125]
	v_mfma_f32_16x16x32_bf16 v[110:113], v[160:163], v[218:221], v[110:113]
	v_mfma_f32_16x16x32_bf16 v[106:109], v[182:185], v[218:221], v[106:109]
	v_mfma_f32_16x16x32_bf16 v[94:97], v[160:163], v[226:229], v[94:97]
	v_mfma_f32_16x16x32_bf16 v[90:93], v[182:185], v[226:229], v[90:93]
	v_mfma_f32_16x16x32_bf16 v[78:81], v[160:163], v[234:237], v[78:81]
	v_mfma_f32_16x16x32_bf16 v[74:77], v[182:185], v[234:237], v[74:77]
	s_setprio 0
	s_setprio 1
	v_mfma_f32_16x16x32_bf16 v[118:121], v[186:189], v[202:205], v[118:121]
	v_mfma_f32_16x16x32_bf16 v[114:117], v[194:197], v[202:205], v[114:117]
	v_mfma_f32_16x16x32_bf16 v[102:105], v[186:189], v[214:217], v[102:105]
	v_mfma_f32_16x16x32_bf16 v[98:101], v[194:197], v[214:217], v[98:101]
	v_mfma_f32_16x16x32_bf16 v[86:89], v[186:189], v[222:225], v[86:89]
	v_mfma_f32_16x16x32_bf16 v[82:85], v[194:197], v[222:225], v[82:85]
	v_mfma_f32_16x16x32_bf16 v[70:73], v[186:189], v[230:233], v[70:73]
	v_mfma_f32_16x16x32_bf16 v[66:69], v[194:197], v[230:233], v[66:69]
	v_mfma_f32_16x16x32_bf16 v[118:121], v[190:193], v[206:209], v[118:121]
	v_mfma_f32_16x16x32_bf16 v[114:117], v[198:201], v[206:209], v[114:117]
	v_mfma_f32_16x16x32_bf16 v[102:105], v[190:193], v[218:221], v[102:105]
	v_mfma_f32_16x16x32_bf16 v[98:101], v[198:201], v[218:221], v[98:101]
	v_mfma_f32_16x16x32_bf16 v[86:89], v[190:193], v[226:229], v[86:89]
	v_mfma_f32_16x16x32_bf16 v[82:85], v[198:201], v[226:229], v[82:85]
	v_mfma_f32_16x16x32_bf16 v[70:73], v[190:193], v[234:237], v[70:73]
	v_mfma_f32_16x16x32_bf16 v[66:69], v[198:201], v[234:237], v[66:69]
	s_setprio 0
	s_barrier
	s_add_i32 s75, s75, s62
	v_lshl_add_u64 v[168:169], s[56:57], 0, v[0:1]
	s_mov_b32 m0, s75
	ds_read_b128 v[202:205], v158 offset:16384
	ds_read_b128 v[206:209], v158 offset:17408
	ds_read_b128 v[214:217], v158 offset:18432
	ds_read_b128 v[218:221], v158 offset:19456
	ds_read_b128 v[222:225], v158 offset:20480
	ds_read_b128 v[226:229], v158 offset:21504
	ds_read_b128 v[230:233], v158 offset:22528
	ds_read_b128 v[234:237], v158 offset:23552
	global_load_lds_dwordx4 v[168:169], off
	s_add_i32 m0, s75, 0x2000
	s_add_u32 s76, s56, 0x80000
	v_lshl_add_u64 v[238:239], s[56:57], 0, v[130:131]
	s_addc_u32 s77, s57, 0
	s_add_i32 s75, s78, s62
	global_load_lds_dwordx4 v[238:239], off
	v_lshl_add_u64 v[240:241], s[76:77], 0, v[0:1]
	s_mov_b32 m0, s75
	v_lshl_add_u64 v[242:243], s[58:59], 0, v[132:133]
	global_load_lds_dwordx4 v[240:241], off
	v_lshl_add_u64 v[240:241], s[76:77], 0, v[130:131]
	s_add_i32 m0, s75, 0x2000
	s_nop 0
	global_load_lds_dwordx4 v[240:241], off
	v_lshl_add_u64 v[240:241], s[58:59], 0, v[134:135]
	s_mov_b32 m0, s63
	s_nop 0
	global_load_lds_dwordx4 v[240:241], off
	s_mov_b32 m0, s64
	s_nop 0
	global_load_lds_dwordx4 v[242:243], off
	s_waitcnt vmcnt(8)
	s_waitcnt lgkmcnt(0)
	s_setprio 1
	s_barrier
; #define PG8_STAGE(bufoff, gbase, voff) do { _Pragma("unroll") for (int _i = 0; _i < 2; ++_i) \
;         __builtin_amdgcn_global_load_lds((const unsigned*)((const char*)(gbase) + (voff)[_i]), (PG8_LAS unsigned*)(lds + (bufoff) + ldsw + _i * 8192), 16, 0, 0); } while (0)
; #define PG8_LDA(dst, b, h) do { _Pragma("unroll") for (int m = 0; m < 4; ++m) _Pragma("unroll") for (int k = 0; k < 2; ++k) dst[m][k] = *(const PG8_LAS bf16x8*)(lds + PG8_SA(b, h) + aoff + m * 2048 + k * 1024); } while (0)
; #define PG8_LDB(dst, b, h) do { _Pragma("unroll") for (int n = 0; n < 2; ++n) _Pragma("unroll") for (int k = 0; k < 2; ++k) dst[n][k] = *(const PG8_LAS bf16x8*)(lds + PG8_SB(b, h) + boff + n * 2048 + k * 1024); } while (0)
; #define PG8_MMA(ai, bj, At, Bt) do { __builtin_amdgcn_s_setprio(1); _Pragma("unroll") for (int m = 0; m < 4; ++m) _Pragma("unroll") for (int n = 0; n < 2; ++n) _Pragma("unroll") for (int k = 0; k < 2; ++k) \
;         acc[ai][bj][m][n] = __builtin_amdgcn_mfma_f32_16x16x32_bf16(Bt[n][k], At[m][k], acc[ai][bj][m][n], 0, 0, 0); __builtin_amdgcn_s_setprio(0); } while (0)
; #define PG8_WAIT_V(n) asm volatile("s_waitcnt vmcnt(" #n ")" ::: "memory")
; #define PG8_WAIT_L(n) asm volatile("s_waitcnt lgkmcnt(" #n ")" ::: "memory")
; #define PG8_BAR __builtin_amdgcn_s_barrier()
; #define PG8_SCHED __builtin_amdgcn_sched_barrier(0)
; template <class Epi, class Sched, bool ALIGN_EPI = false, bool SP2 = false>
; __device__ __forceinline__ void gemm_phase(PG8_LAS unsigned char* lds, const Gemm g, const Sched& S, const Epi& E) {
;     ...
;             PG8_WAIT_V(8); PG8_WAIT_L(0); PG8_BAR; PG8_MMA(1, 0, At, B0); PG8_MMA(1, 1, At, B1); PG8_BAR; PG8_SCHED;
;             PG8_LDB(B0, 1, 0); PG8_LDB(B1, 1, 1); PG8_SCHED; PG8_LDA(At, 1, 0); PG8_STAGE(PG8_SA(0, 1), a2 + hstep, voffA);
;             PG8_WAIT_V(8); PG8_WAIT_L(0); PG8_BAR; PG8_MMA(0, 0, At, B0); PG8_MMA(0, 1, At, B1); PG8_BAR; PG8_SCHED;
	v_mfma_f32_16x16x32_bf16 v[62:65], v[152:155], v[202:205], v[62:65]
	v_mfma_f32_16x16x32_bf16 v[58:61], v[164:167], v[202:205], v[58:61]
	v_mfma_f32_16x16x32_bf16 v[46:49], v[152:155], v[214:217], v[46:49]
	v_mfma_f32_16x16x32_bf16 v[42:45], v[164:167], v[214:217], v[42:45]
	v_mfma_f32_16x16x32_bf16 v[30:33], v[152:155], v[222:225], v[30:33]
	v_mfma_f32_16x16x32_bf16 v[26:29], v[164:167], v[222:225], v[26:29]
	v_mfma_f32_16x16x32_bf16 v[14:17], v[152:155], v[230:233], v[14:17]
	v_mfma_f32_16x16x32_bf16 v[10:13], v[164:167], v[230:233], v[10:13]
	v_mfma_f32_16x16x32_bf16 v[62:65], v[160:163], v[206:209], v[62:65]
	v_mfma_f32_16x16x32_bf16 v[58:61], v[182:185], v[206:209], v[58:61]
	v_mfma_f32_16x16x32_bf16 v[46:49], v[160:163], v[218:221], v[46:49]
	v_mfma_f32_16x16x32_bf16 v[42:45], v[182:185], v[218:221], v[42:45]
	v_mfma_f32_16x16x32_bf16 v[30:33], v[160:163], v[226:229], v[30:33]
	v_mfma_f32_16x16x32_bf16 v[26:29], v[182:185], v[226:229], v[26:29]
	v_mfma_f32_16x16x32_bf16 v[14:17], v[160:163], v[234:237], v[14:17]
	v_mfma_f32_16x16x32_bf16 v[10:13], v[182:185], v[234:237], v[10:13]
	s_setprio 0
	s_setprio 1
	v_mfma_f32_16x16x32_bf16 v[54:57], v[186:189], v[202:205], v[54:57]
	v_mfma_f32_16x16x32_bf16 v[50:53], v[194:197], v[202:205], v[50:53]
	v_mfma_f32_16x16x32_bf16 v[38:41], v[186:189], v[214:217], v[38:41]
	v_mfma_f32_16x16x32_bf16 v[34:37], v[194:197], v[214:217], v[34:37]
	v_mfma_f32_16x16x32_bf16 v[22:25], v[186:189], v[222:225], v[22:25]
	v_mfma_f32_16x16x32_bf16 v[18:21], v[194:197], v[222:225], v[18:21]
	v_mfma_f32_16x16x32_bf16 v[6:9], v[186:189], v[230:233], v[6:9]
	v_mfma_f32_16x16x32_bf16 v[2:5], v[194:197], v[230:233], v[2:5]
	v_mfma_f32_16x16x32_bf16 v[54:57], v[190:193], v[206:209], v[54:57]
	v_mfma_f32_16x16x32_bf16 v[50:53], v[198:201], v[206:209], v[50:53]
	v_mfma_f32_16x16x32_bf16 v[38:41], v[190:193], v[218:221], v[38:41]
	v_mfma_f32_16x16x32_bf16 v[34:37], v[198:201], v[218:221], v[34:37]
	v_mfma_f32_16x16x32_bf16 v[22:25], v[190:193], v[226:229], v[22:25]
	v_mfma_f32_16x16x32_bf16 v[18:21], v[198:201], v[226:229], v[18:21]
	v_mfma_f32_16x16x32_bf16 v[6:9], v[190:193], v[234:237], v[6:9]
	v_mfma_f32_16x16x32_bf16 v[2:5], v[198:201], v[234:237], v[2:5]
	s_setprio 0
	s_barrier
	s_add_i32 s75, 0, 0x18000
	v_add_u32_e32 v142, s75, v156
	s_add_i32 s76, 0, 0x1c000
	ds_read_b128 v[152:155], v142
	ds_read_b128 v[160:163], v142 offset:1024
	ds_read_b128 v[164:167], v142 offset:2048
	ds_read_b128 v[182:185], v142 offset:3072
	v_add_u32_e32 v142, s76, v156
	ds_read_b128 v[186:189], v142
	ds_read_b128 v[190:193], v142 offset:1024
	ds_read_b128 v[194:197], v142 offset:2048
	ds_read_b128 v[198:201], v142 offset:3072
	s_add_u32 s58, s58, 0x80000
	s_addc_u32 s59, s59, 0
	s_mov_b32 m0, s65
	v_lshl_add_u64 v[244:245], s[58:59], 0, v[134:135]
	ds_read_b128 v[202:205], v158 offset:32768
	ds_read_b128 v[206:209], v158 offset:33792
	ds_read_b128 v[214:217], v158 offset:34816
	ds_read_b128 v[218:221], v158 offset:35840
	ds_read_b128 v[222:225], v158 offset:36864
	ds_read_b128 v[226:229], v158 offset:37888
	ds_read_b128 v[230:233], v158 offset:38912
	ds_read_b128 v[234:237], v158 offset:39936
	global_load_lds_dwordx4 v[244:245], off
	v_lshl_add_u64 v[244:245], s[58:59], 0, v[132:133]
	s_mov_b32 m0, s66
	s_nop 0
	global_load_lds_dwordx4 v[244:245], off
	s_waitcnt vmcnt(8)
	s_waitcnt lgkmcnt(0)
	s_setprio 1
	s_barrier
	v_mfma_f32_16x16x32_bf16 v[126:129], v[152:155], v[202:205], v[126:129]
	v_mfma_f32_16x16x32_bf16 v[122:125], v[164:167], v[202:205], v[122:125]
	v_mfma_f32_16x16x32_bf16 v[110:113], v[152:155], v[214:217], v[110:113]
	v_mfma_f32_16x16x32_bf16 v[106:109], v[164:167], v[214:217], v[106:109]
	v_mfma_f32_16x16x32_bf16 v[94:97], v[152:155], v[222:225], v[94:97]
	v_mfma_f32_16x16x32_bf16 v[90:93], v[164:167], v[222:225], v[90:93]
	v_mfma_f32_16x16x32_bf16 v[78:81], v[152:155], v[230:233], v[78:81]
	v_mfma_f32_16x16x32_bf16 v[74:77], v[164:167], v[230:233], v[74:77]
	v_mfma_f32_16x16x32_bf16 v[126:129], v[160:163], v[206:209], v[126:129]
	v_mfma_f32_16x16x32_bf16 v[122:125], v[182:185], v[206:209], v[122:125]
	v_mfma_f32_16x16x32_bf16 v[110:113], v[160:163], v[218:221], v[110:113]
	v_mfma_f32_16x16x32_bf16 v[106:109], v[182:185], v[218:221], v[106:109]
	v_mfma_f32_16x16x32_bf16 v[94:97], v[160:163], v[226:229], v[94:97]
	v_mfma_f32_16x16x32_bf16 v[90:93], v[182:185], v[226:229], v[90:93]
	v_mfma_f32_16x16x32_bf16 v[78:81], v[160:163], v[234:237], v[78:81]
	v_mfma_f32_16x16x32_bf16 v[74:77], v[182:185], v[234:237], v[74:77]
	s_setprio 0
	s_setprio 1
	v_mfma_f32_16x16x32_bf16 v[118:121], v[186:189], v[202:205], v[118:121]
	v_mfma_f32_16x16x32_bf16 v[114:117], v[194:197], v[202:205], v[114:117]
	v_mfma_f32_16x16x32_bf16 v[102:105], v[186:189], v[214:217], v[102:105]
	v_mfma_f32_16x16x32_bf16 v[98:101], v[194:197], v[214:217], v[98:101]
	v_mfma_f32_16x16x32_bf16 v[86:89], v[186:189], v[222:225], v[86:89]
	v_mfma_f32_16x16x32_bf16 v[82:85], v[194:197], v[222:225], v[82:85]
	v_mfma_f32_16x16x32_bf16 v[70:73], v[186:189], v[230:233], v[70:73]
	v_mfma_f32_16x16x32_bf16 v[66:69], v[194:197], v[230:233], v[66:69]
	v_mfma_f32_16x16x32_bf16 v[118:121], v[190:193], v[206:209], v[118:121]
	v_mfma_f32_16x16x32_bf16 v[114:117], v[198:201], v[206:209], v[114:117]
	v_mfma_f32_16x16x32_bf16 v[102:105], v[190:193], v[218:221], v[102:105]
	v_mfma_f32_16x16x32_bf16 v[98:101], v[198:201], v[218:221], v[98:101]
	v_mfma_f32_16x16x32_bf16 v[86:89], v[190:193], v[226:229], v[86:89]
	v_mfma_f32_16x16x32_bf16 v[82:85], v[198:201], v[226:229], v[82:85]
	v_mfma_f32_16x16x32_bf16 v[70:73], v[190:193], v[234:237], v[70:73]
	v_mfma_f32_16x16x32_bf16 v[66:69], v[198:201], v[234:237], v[66:69]
	s_setprio 0
	s_barrier
; #define PG8_STAGE(bufoff, gbase, voff) do { _Pragma("unroll") for (int _i = 0; _i < 2; ++_i) \
;         __builtin_amdgcn_global_load_lds((const unsigned*)((const char*)(gbase) + (voff)[_i]), (PG8_LAS unsigned*)(lds + (bufoff) + ldsw + _i * 8192), 16, 0, 0); } while (0)
; #define PG8_LDA(dst, b, h) do { _Pragma("unroll") for (int m = 0; m < 4; ++m) _Pragma("unroll") for (int k = 0; k < 2; ++k) dst[m][k] = *(const PG8_LAS bf16x8*)(lds + PG8_SA(b, h) + aoff + m * 2048 + k * 1024); } while (0)
; #define PG8_MMA(ai, bj, At, Bt) do { __builtin_amdgcn_s_setprio(1); _Pragma("unroll") for (int m = 0; m < 4; ++m) _Pragma("unroll") for (int n = 0; n < 2; ++n) _Pragma("unroll") for (int k = 0; k < 2; ++k) \
;         acc[ai][bj][m][n] = __builtin_amdgcn_mfma_f32_16x16x32_bf16(Bt[n][k], At[m][k], acc[ai][bj][m][n], 0, 0, 0); __builtin_amdgcn_s_setprio(0); } while (0)
; #define PG8_WAIT_V(n) asm volatile("s_waitcnt vmcnt(" #n ")" ::: "memory")
; #define PG8_WAIT_L(n) asm volatile("s_waitcnt lgkmcnt(" #n ")" ::: "memory")
; #define PG8_BAR __builtin_amdgcn_s_barrier()
; #define PG8_SCHED __builtin_amdgcn_sched_barrier(0)
; template <class Epi, class Sched, bool ALIGN_EPI = false, bool SP2 = false>
; __device__ __forceinline__ void gemm_phase(PG8_LAS unsigned char* lds, const Gemm g, const Sched& S, const Epi& E) {
;     ...
;         for (int t = 0; t < nt; t += 2) {
;             const bool last = (t == nt - 2);
;     ...
;             PG8_LDA(At, 1, 1); PG8_STAGE(PG8_SB(1, 0), b3, voffB); PG8_STAGE(PG8_SB(1, 1), b3 + hstep, voffB); PG8_STAGE(PG8_SA(1, 0), a3, voffA);
;             PG8_WAIT_V(8); PG8_WAIT_L(0); PG8_BAR; PG8_MMA(1, 0, At, B0); PG8_MMA(1, 1, At, B1); PG8_BAR; PG8_SCHED;
	s_add_i32 s58, s75, s62
	v_lshl_add_u64 v[168:169], v[168:169], 0, s[34:35]
	s_mov_b32 m0, s58
	ds_read_b128 v[202:205], v158 offset:49152
	ds_read_b128 v[206:209], v158 offset:50176
	ds_read_b128 v[214:217], v158 offset:51200
	ds_read_b128 v[218:221], v158 offset:52224
	ds_read_b128 v[222:225], v158 offset:53248
	ds_read_b128 v[226:229], v158 offset:54272
	ds_read_b128 v[230:233], v158 offset:55296
	ds_read_b128 v[234:237], v158 offset:56320
	global_load_lds_dwordx4 v[168:169], off
	s_add_i32 m0, s58, 0x2000
	s_add_u32 s56, s56, 0x80080
	v_lshl_add_u64 v[168:169], v[238:239], 0, s[34:35]
	s_addc_u32 s57, s57, 0
	s_add_i32 s58, s76, s62
	global_load_lds_dwordx4 v[168:169], off
	v_lshl_add_u64 v[168:169], s[56:57], 0, v[0:1]
	s_mov_b32 m0, s58
	s_nop 0
	global_load_lds_dwordx4 v[168:169], off
	v_lshl_add_u64 v[168:169], s[56:57], 0, v[130:131]
	s_add_i32 m0, s58, 0x2000
	s_nop 0
	global_load_lds_dwordx4 v[168:169], off
	v_lshl_add_u64 v[168:169], v[240:241], 0, s[34:35]
	s_mov_b32 m0, s67
	s_nop 0
	global_load_lds_dwordx4 v[168:169], off
	v_lshl_add_u64 v[168:169], v[242:243], 0, s[34:35]
	s_mov_b32 m0, s68
	s_nop 0
	global_load_lds_dwordx4 v[168:169], off
	s_waitcnt vmcnt(8)
	s_waitcnt lgkmcnt(0)
	s_setprio 1
	s_barrier
	v_mfma_f32_16x16x32_bf16 v[62:65], v[152:155], v[202:205], v[62:65]
	v_mfma_f32_16x16x32_bf16 v[58:61], v[164:167], v[202:205], v[58:61]
	v_mfma_f32_16x16x32_bf16 v[46:49], v[152:155], v[214:217], v[46:49]
	v_mfma_f32_16x16x32_bf16 v[42:45], v[164:167], v[214:217], v[42:45]
	v_mfma_f32_16x16x32_bf16 v[30:33], v[152:155], v[222:225], v[30:33]
	v_mfma_f32_16x16x32_bf16 v[26:29], v[164:167], v[222:225], v[26:29]
	v_mfma_f32_16x16x32_bf16 v[14:17], v[152:155], v[230:233], v[14:17]
	v_mfma_f32_16x16x32_bf16 v[10:13], v[164:167], v[230:233], v[10:13]
	v_mfma_f32_16x16x32_bf16 v[62:65], v[160:163], v[206:209], v[62:65]
	v_mfma_f32_16x16x32_bf16 v[58:61], v[182:185], v[206:209], v[58:61]
	v_mfma_f32_16x16x32_bf16 v[46:49], v[160:163], v[218:221], v[46:49]
	v_mfma_f32_16x16x32_bf16 v[42:45], v[182:185], v[218:221], v[42:45]
	v_mfma_f32_16x16x32_bf16 v[30:33], v[160:163], v[226:229], v[30:33]
	v_mfma_f32_16x16x32_bf16 v[26:29], v[182:185], v[226:229], v[26:29]
	v_mfma_f32_16x16x32_bf16 v[14:17], v[160:163], v[234:237], v[14:17]
	v_mfma_f32_16x16x32_bf16 v[10:13], v[182:185], v[234:237], v[10:13]
	s_setprio 0
	s_setprio 1
	v_mfma_f32_16x16x32_bf16 v[54:57], v[186:189], v[202:205], v[54:57]
	v_mfma_f32_16x16x32_bf16 v[50:53], v[194:197], v[202:205], v[50:53]
	v_mfma_f32_16x16x32_bf16 v[38:41], v[186:189], v[214:217], v[38:41]
	v_mfma_f32_16x16x32_bf16 v[34:37], v[194:197], v[214:217], v[34:37]
	v_mfma_f32_16x16x32_bf16 v[22:25], v[186:189], v[222:225], v[22:25]
	v_mfma_f32_16x16x32_bf16 v[18:21], v[194:197], v[222:225], v[18:21]
	v_mfma_f32_16x16x32_bf16 v[6:9], v[186:189], v[230:233], v[6:9]
	v_mfma_f32_16x16x32_bf16 v[2:5], v[194:197], v[230:233], v[2:5]
	v_mfma_f32_16x16x32_bf16 v[54:57], v[190:193], v[206:209], v[54:57]
	v_mfma_f32_16x16x32_bf16 v[50:53], v[198:201], v[206:209], v[50:53]
	v_mfma_f32_16x16x32_bf16 v[38:41], v[190:193], v[218:221], v[38:41]
	v_mfma_f32_16x16x32_bf16 v[34:37], v[198:201], v[218:221], v[34:37]
	v_mfma_f32_16x16x32_bf16 v[22:25], v[190:193], v[226:229], v[22:25]
	v_mfma_f32_16x16x32_bf16 v[18:21], v[198:201], v[226:229], v[18:21]
	v_mfma_f32_16x16x32_bf16 v[6:9], v[190:193], v[234:237], v[6:9]
	v_mfma_f32_16x16x32_bf16 v[2:5], v[198:201], v[234:237], v[2:5]
	s_setprio 0
	s_add_i32 s74, s74, 2
	s_add_u32 s72, s72, 0x100
	s_addc_u32 s73, s73, 0
	s_add_u32 s40, s40, 0x100
	s_addc_u32 s41, s41, 0
	s_cmp_gt_u32 s74, 29
	s_cbranch_scc0 .Lg1_head_bar
	s_barrier
	v_mbcnt_lo_u32_b32 v221, -1, 0
	v_mbcnt_hi_u32_b32 v221, -1, v221
	v_and_b32_e32 v220, 3, v221
	v_and_b32_e32 v221, 60, v221
	v_lshl_or_b32 v220, v220, 6, v221
	s_and_b64 vcc, exec, s[44:45]
	s_cbranch_vccz .LBB0_421
	s_barrier

; __device__ __forceinline__ unsigned cvt_pk_bf16(float lo, float hi) { unsigned r; asm volatile("v_cvt_pk_bf16_f32 %0, %1, %2" : "=v"(r) : "v"(lo), "v"(hi)); return r; }
; __device__ __forceinline__ float fsig(float x) { return __builtin_amdgcn_rcpf(1.0f + __expf(-x)); }
;     __device__ __forceinline__ void operator()(const f32x4 (&acc)[2][2][4][2], const Unit& u, int wr, int wc, int fr, int fq) const {
;         const int pn = u.pn;
;         const int act = (pn >= 33) ? 2 : 0;
;         const int row0 = u.pm * BM + wr * 64 + fr, col0 = pn * BM + wc * 32 + 8 * fq;
; #pragma unroll
;         for (int ai = 0; ai < 2; ++ai)
; #pragma unroll
;             for (int m = 0; m < 4; ++m) { bf16_t* rowp = O + (size_t)(row0 + ai * HALF + m * 16) * LDP + col0;
; #pragma unroll
;                 for (int bj = 0; bj < 2; ++bj) { f32x4 v0 = acc[ai][bj][m][0], v1 = acc[ai][bj][m][1];
;                     if (act == 1) {
; #pragma unroll
;                         for (int j = 0; j < 4; ++j) { v0[j] = v0[j] * fsig(v0[j]); v1[j] = v1[j] * fsig(v1[j]); } }
;                     else if (act == 2) {
; #pragma unroll
;                         for (int j = 0; j < 4; ++j) { v0[j] = fsig(v0[j]); v1[j] = fsig(v1[j]); } }
;                     u32x4 w; w.x = cvt_pk_bf16(v0[0], v0[1]); w.y = cvt_pk_bf16(v0[2], v0[3]); w.z = cvt_pk_bf16(v1[0], v1[1]); w.w = cvt_pk_bf16(v1[2], v1[3]);
;                     *(u32x4*)(rowp + bj * HALF) = w; } }
.LBB0_423:
	v_lshl_add_u32 v159, s71, 8, v138
	v_lshl_or_b32 v152, s70, 8, v157
	v_mov_b64_e32 v[154:155], s[42:43]
	v_ashrrev_i32_e32 v153, 31, v152
	v_mad_i64_i32 v[154:155], s[2:3], v159, s7, v[154:155]
	v_cvt_pk_bf16_f32 v126, v126, v127
	v_cvt_pk_bf16_f32 v127, v128, v129
	v_cvt_pk_bf16_f32 v128, v122, v123
	v_cndmask_b32_e64 v122, 0, 1, s[56:57]
	v_lshl_add_u64 v[154:155], v[152:153], 1, v[154:155]
	v_cmp_ne_u32_e64 s[40:41], 1, v122
	s_andn2_b64 vcc, exec, s[56:57]
	v_cvt_pk_bf16_f32 v129, v124, v125
	ds_bpermute_b32 v222, v220, v154
	ds_bpermute_b32 v223, v220, v155
	ds_bpermute_b32 v126, v220, v126
	ds_bpermute_b32 v127, v220, v127
	ds_bpermute_b32 v128, v220, v128
	ds_bpermute_b32 v129, v220, v129
	s_waitcnt lgkmcnt(0)
	global_store_dwordx4 v[222:223], v[126:129], off sc1
	s_cbranch_vccnz .LBB0_425
	v_mul_f32_e32 v118, 0xbfb8aa3b, v118
	v_mul_f32_e32 v114, 0xbfb8aa3b, v114
	v_mul_f32_e32 v119, 0xbfb8aa3b, v119
	v_mul_f32_e32 v115, 0xbfb8aa3b, v115
	v_mul_f32_e32 v120, 0xbfb8aa3b, v120
	v_mul_f32_e32 v116, 0xbfb8aa3b, v116
	v_mul_f32_e32 v121, 0xbfb8aa3b, v121
	v_mul_f32_e32 v117, 0xbfb8aa3b, v117
	v_exp_f32_e32 v118, v118
	v_exp_f32_e32 v114, v114
	v_exp_f32_e32 v119, v119
	v_exp_f32_e32 v115, v115
	v_exp_f32_e32 v120, v120
	v_exp_f32_e32 v116, v116
	v_exp_f32_e32 v121, v121
	v_exp_f32_e32 v117, v117
	v_add_f32_e32 v118, 1.0, v118
	v_add_f32_e32 v114, 1.0, v114
	v_add_f32_e32 v119, 1.0, v119
	v_add_f32_e32 v115, 1.0, v115
	v_add_f32_e32 v120, 1.0, v120
	v_add_f32_e32 v116, 1.0, v116
	v_add_f32_e32 v121, 1.0, v121
	v_add_f32_e32 v117, 1.0, v117
	v_rcp_f32_e32 v118, v118
	v_rcp_f32_e32 v114, v114
	v_rcp_f32_e32 v119, v119
	v_rcp_f32_e32 v115, v115
	v_rcp_f32_e32 v120, v120
	v_rcp_f32_e32 v116, v116
	v_rcp_f32_e32 v121, v121
	v_rcp_f32_e32 v117, v117
.LBB0_425:
	v_readlane_b32 s78, v253, 49
	s_and_b64 vcc, exec, s[40:41]
	s_mov_b32 s75, 0x800000
	s_mov_b32 s76, 0x1ffff
	v_readlane_b32 s79, v253, 50
	v_cvt_pk_bf16_f32 v118, v118, v119
	v_cvt_pk_bf16_f32 v119, v120, v121
	v_cvt_pk_bf16_f32 v120, v114, v115
	v_cvt_pk_bf16_f32 v121, v116, v117
	ds_bpermute_b32 v222, v220, v154
	ds_bpermute_b32 v223, v220, v155
	ds_bpermute_b32 v118, v220, v118
	ds_bpermute_b32 v119, v220, v119
	ds_bpermute_b32 v120, v220, v120
	ds_bpermute_b32 v121, v220, v121
	s_waitcnt lgkmcnt(0)
	global_store_dwordx4 v[222:223], v[118:121], off offset:256 sc1
	s_cbranch_vccnz .LBB0_427
	v_mul_f32_e32 v110, 0xbfb8aa3b, v110
	v_mul_f32_e32 v106, 0xbfb8aa3b, v106
	v_mul_f32_e32 v111, 0xbfb8aa3b, v111
	v_mul_f32_e32 v107, 0xbfb8aa3b, v107
	v_mul_f32_e32 v112, 0xbfb8aa3b, v112
	v_mul_f32_e32 v108, 0xbfb8aa3b, v108
	v_mul_f32_e32 v113, 0xbfb8aa3b, v113
	v_mul_f32_e32 v109, 0xbfb8aa3b, v109
	v_exp_f32_e32 v110, v110
	v_exp_f32_e32 v106, v106
	v_exp_f32_e32 v111, v111
	v_exp_f32_e32 v107, v107
	v_exp_f32_e32 v112, v112
	v_exp_f32_e32 v108, v108
	v_exp_f32_e32 v113, v113
	v_exp_f32_e32 v109, v109
	v_add_f32_e32 v110, 1.0, v110
	v_add_f32_e32 v106, 1.0, v106
	v_add_f32_e32 v111, 1.0, v111
	v_add_f32_e32 v107, 1.0, v107
	v_add_f32_e32 v112, 1.0, v112
	v_add_f32_e32 v108, 1.0, v108
	v_add_f32_e32 v113, 1.0, v113
	v_add_f32_e32 v109, 1.0, v109
	v_rcp_f32_e32 v110, v110
	v_rcp_f32_e32 v106, v106
	v_rcp_f32_e32 v111, v111
	v_rcp_f32_e32 v107, v107
	v_rcp_f32_e32 v112, v112
	v_rcp_f32_e32 v108, v108
	v_rcp_f32_e32 v113, v113
	v_rcp_f32_e32 v109, v109
.LBB0_427:
	v_or_b32_e32 v116, 16, v159
	v_mov_b64_e32 v[114:115], s[42:43]
	v_mad_i64_i32 v[114:115], s[2:3], v116, s7, v[114:115]
	v_lshl_add_u64 v[114:115], v[152:153], 1, v[114:115]
	s_and_b64 vcc, exec, s[40:41]
	v_cvt_pk_bf16_f32 v110, v110, v111
	v_cvt_pk_bf16_f32 v111, v112, v113
	v_cvt_pk_bf16_f32 v112, v106, v107
	v_cvt_pk_bf16_f32 v113, v108, v109
	ds_bpermute_b32 v222, v220, v114
	ds_bpermute_b32 v223, v220, v115
	ds_bpermute_b32 v110, v220, v110
	ds_bpermute_b32 v111, v220, v111
	ds_bpermute_b32 v112, v220, v112
	ds_bpermute_b32 v113, v220, v113
	s_waitcnt lgkmcnt(0)
	global_store_dwordx4 v[222:223], v[110:113], off sc1
	s_cbranch_vccnz .LBB0_429
	v_mul_f32_e32 v102, 0xbfb8aa3b, v102
	v_mul_f32_e32 v98, 0xbfb8aa3b, v98
	v_mul_f32_e32 v103, 0xbfb8aa3b, v103
	v_mul_f32_e32 v99, 0xbfb8aa3b, v99
	v_mul_f32_e32 v104, 0xbfb8aa3b, v104
	v_mul_f32_e32 v100, 0xbfb8aa3b, v100
	v_mul_f32_e32 v105, 0xbfb8aa3b, v105
	v_mul_f32_e32 v101, 0xbfb8aa3b, v101
	v_exp_f32_e32 v102, v102
	v_exp_f32_e32 v98, v98
	v_exp_f32_e32 v103, v103
	v_exp_f32_e32 v99, v99
	v_exp_f32_e32 v104, v104
	v_exp_f32_e32 v100, v100
	v_exp_f32_e32 v105, v105
	v_exp_f32_e32 v101, v101
	v_add_f32_e32 v102, 1.0, v102
	v_add_f32_e32 v98, 1.0, v98
	v_add_f32_e32 v103, 1.0, v103
	v_add_f32_e32 v99, 1.0, v99
	v_add_f32_e32 v104, 1.0, v104
	v_add_f32_e32 v100, 1.0, v100
	v_add_f32_e32 v105, 1.0, v105
	v_add_f32_e32 v101, 1.0, v101
	v_rcp_f32_e32 v102, v102
	v_rcp_f32_e32 v98, v98
	v_rcp_f32_e32 v103, v103
	v_rcp_f32_e32 v99, v99
	v_rcp_f32_e32 v104, v104
	v_rcp_f32_e32 v100, v100
	v_rcp_f32_e32 v105, v105
	v_rcp_f32_e32 v101, v101
; __device__ __forceinline__ unsigned cvt_pk_bf16(float lo, float hi) { unsigned r; asm volatile("v_cvt_pk_bf16_f32 %0, %1, %2" : "=v"(r) : "v"(lo), "v"(hi)); return r; }
; __device__ __forceinline__ float fsig(float x) { return __builtin_amdgcn_rcpf(1.0f + __expf(-x)); }
;     __device__ __forceinline__ void operator()(const f32x4 (&acc)[2][2][4][2], const Unit& u, int wr, int wc, int fr, int fq) const {
;         const int pn = u.pn;
;         const int act = (pn >= 33) ? 2 : 0;
;         const int row0 = u.pm * BM + wr * 64 + fr, col0 = pn * BM + wc * 32 + 8 * fq;
; #pragma unroll
;         for (int ai = 0; ai < 2; ++ai)
; #pragma unroll
;             for (int m = 0; m < 4; ++m) { bf16_t* rowp = O + (size_t)(row0 + ai * HALF + m * 16) * LDP + col0;
; #pragma unroll
;                 for (int bj = 0; bj < 2; ++bj) { f32x4 v0 = acc[ai][bj][m][0], v1 = acc[ai][bj][m][1];
;                     if (act == 1) {
; #pragma unroll
;                         for (int j = 0; j < 4; ++j) { v0[j] = v0[j] * fsig(v0[j]); v1[j] = v1[j] * fsig(v1[j]); } }
;                     else if (act == 2) {
; #pragma unroll
;                         for (int j = 0; j < 4; ++j) { v0[j] = fsig(v0[j]); v1[j] = fsig(v1[j]); } }
;                     u32x4 w; w.x = cvt_pk_bf16(v0[0], v0[1]); w.y = cvt_pk_bf16(v0[2], v0[3]); w.z = cvt_pk_bf16(v1[0], v1[1]); w.w = cvt_pk_bf16(v1[2], v1[3]);
;                     *(u32x4*)(rowp + bj * HALF) = w; } }
.LBB0_429:
	s_and_b64 vcc, exec, s[40:41]
	v_cvt_pk_bf16_f32 v102, v102, v103
	v_cvt_pk_bf16_f32 v103, v104, v105
	v_cvt_pk_bf16_f32 v104, v98, v99
	v_cvt_pk_bf16_f32 v105, v100, v101
	ds_bpermute_b32 v222, v220, v114
	ds_bpermute_b32 v223, v220, v115
	ds_bpermute_b32 v102, v220, v102
	ds_bpermute_b32 v103, v220, v103
	ds_bpermute_b32 v104, v220, v104
	ds_bpermute_b32 v105, v220, v105
	s_waitcnt lgkmcnt(0)
	global_store_dwordx4 v[222:223], v[102:105], off offset:256 sc1
	s_cbranch_vccnz .LBB0_431
	v_mul_f32_e32 v94, 0xbfb8aa3b, v94
	v_mul_f32_e32 v90, 0xbfb8aa3b, v90
	v_mul_f32_e32 v95, 0xbfb8aa3b, v95
	v_mul_f32_e32 v91, 0xbfb8aa3b, v91
	v_mul_f32_e32 v96, 0xbfb8aa3b, v96
	v_mul_f32_e32 v92, 0xbfb8aa3b, v92
	v_mul_f32_e32 v97, 0xbfb8aa3b, v97
	v_mul_f32_e32 v93, 0xbfb8aa3b, v93
	v_exp_f32_e32 v94, v94
	v_exp_f32_e32 v90, v90
	v_exp_f32_e32 v95, v95
	v_exp_f32_e32 v91, v91
	v_exp_f32_e32 v96, v96
	v_exp_f32_e32 v92, v92
	v_exp_f32_e32 v97, v97
	v_exp_f32_e32 v93, v93
	v_add_f32_e32 v94, 1.0, v94
	v_add_f32_e32 v90, 1.0, v90
	v_add_f32_e32 v95, 1.0, v95
	v_add_f32_e32 v91, 1.0, v91
	v_add_f32_e32 v96, 1.0, v96
	v_add_f32_e32 v92, 1.0, v92
	v_add_f32_e32 v97, 1.0, v97
	v_add_f32_e32 v93, 1.0, v93
	v_rcp_f32_e32 v94, v94
	v_rcp_f32_e32 v90, v90
	v_rcp_f32_e32 v95, v95
	v_rcp_f32_e32 v91, v91
	v_rcp_f32_e32 v96, v96
	v_rcp_f32_e32 v92, v92
	v_rcp_f32_e32 v97, v97
	v_rcp_f32_e32 v93, v93
.LBB0_431:
	v_or_b32_e32 v100, 32, v159
	v_mov_b64_e32 v[98:99], s[42:43]
	v_mad_i64_i32 v[98:99], s[2:3], v100, s7, v[98:99]
	v_lshl_add_u64 v[98:99], v[152:153], 1, v[98:99]
	s_and_b64 vcc, exec, s[40:41]
	v_cvt_pk_bf16_f32 v94, v94, v95
	v_cvt_pk_bf16_f32 v95, v96, v97
	v_cvt_pk_bf16_f32 v96, v90, v91
	v_cvt_pk_bf16_f32 v97, v92, v93
	ds_bpermute_b32 v222, v220, v98
	ds_bpermute_b32 v223, v220, v99
	ds_bpermute_b32 v94, v220, v94
	ds_bpermute_b32 v95, v220, v95
	ds_bpermute_b32 v96, v220, v96
	ds_bpermute_b32 v97, v220, v97
	s_waitcnt lgkmcnt(0)
	global_store_dwordx4 v[222:223], v[94:97], off sc1
	s_cbranch_vccnz .LBB0_433
	v_mul_f32_e32 v86, 0xbfb8aa3b, v86
	v_mul_f32_e32 v82, 0xbfb8aa3b, v82
	v_mul_f32_e32 v87, 0xbfb8aa3b, v87
	v_mul_f32_e32 v83, 0xbfb8aa3b, v83
	v_mul_f32_e32 v88, 0xbfb8aa3b, v88
	v_mul_f32_e32 v84, 0xbfb8aa3b, v84
	v_mul_f32_e32 v89, 0xbfb8aa3b, v89
	v_mul_f32_e32 v85, 0xbfb8aa3b, v85
	v_exp_f32_e32 v86, v86
	v_exp_f32_e32 v82, v82
	v_exp_f32_e32 v87, v87
	v_exp_f32_e32 v83, v83
	v_exp_f32_e32 v88, v88
	v_exp_f32_e32 v84, v84
	v_exp_f32_e32 v89, v89
	v_exp_f32_e32 v85, v85
	v_add_f32_e32 v86, 1.0, v86
	v_add_f32_e32 v82, 1.0, v82
	v_add_f32_e32 v87, 1.0, v87
	v_add_f32_e32 v83, 1.0, v83
	v_add_f32_e32 v88, 1.0, v88
	v_add_f32_e32 v84, 1.0, v84
	v_add_f32_e32 v89, 1.0, v89
	v_add_f32_e32 v85, 1.0, v85
	v_rcp_f32_e32 v86, v86
	v_rcp_f32_e32 v82, v82
	v_rcp_f32_e32 v87, v87
	v_rcp_f32_e32 v83, v83
	v_rcp_f32_e32 v88, v88
	v_rcp_f32_e32 v84, v84
	v_rcp_f32_e32 v89, v89
	v_rcp_f32_e32 v85, v85
.LBB0_433:
	s_and_b64 vcc, exec, s[40:41]
	v_cvt_pk_bf16_f32 v86, v86, v87
	v_cvt_pk_bf16_f32 v87, v88, v89
	v_cvt_pk_bf16_f32 v88, v82, v83
	v_cvt_pk_bf16_f32 v89, v84, v85
	ds_bpermute_b32 v222, v220, v98
	ds_bpermute_b32 v223, v220, v99
	ds_bpermute_b32 v86, v220, v86
	ds_bpermute_b32 v87, v220, v87
	ds_bpermute_b32 v88, v220, v88
	ds_bpermute_b32 v89, v220, v89
	s_waitcnt lgkmcnt(0)
	global_store_dwordx4 v[222:223], v[86:89], off offset:256 sc1
	s_cbranch_vccnz .LBB0_435
	v_mul_f32_e32 v78, 0xbfb8aa3b, v78
	v_mul_f32_e32 v74, 0xbfb8aa3b, v74
	v_mul_f32_e32 v79, 0xbfb8aa3b, v79
	v_mul_f32_e32 v75, 0xbfb8aa3b, v75
	v_mul_f32_e32 v80, 0xbfb8aa3b, v80
	v_mul_f32_e32 v76, 0xbfb8aa3b, v76
	v_mul_f32_e32 v81, 0xbfb8aa3b, v81
	v_mul_f32_e32 v77, 0xbfb8aa3b, v77
	v_exp_f32_e32 v78, v78
	v_exp_f32_e32 v74, v74
	v_exp_f32_e32 v79, v79
	v_exp_f32_e32 v75, v75
	v_exp_f32_e32 v80, v80
	v_exp_f32_e32 v76, v76
	v_exp_f32_e32 v81, v81
	v_exp_f32_e32 v77, v77
	v_add_f32_e32 v78, 1.0, v78
	v_add_f32_e32 v74, 1.0, v74
	v_add_f32_e32 v79, 1.0, v79
	v_add_f32_e32 v75, 1.0, v75
	v_add_f32_e32 v80, 1.0, v80
	v_add_f32_e32 v76, 1.0, v76
	v_add_f32_e32 v81, 1.0, v81
	v_add_f32_e32 v77, 1.0, v77
	v_rcp_f32_e32 v78, v78
	v_rcp_f32_e32 v74, v74
	v_rcp_f32_e32 v79, v79
	v_rcp_f32_e32 v75, v75
	v_rcp_f32_e32 v80, v80
	v_rcp_f32_e32 v76, v76
	v_rcp_f32_e32 v81, v81
	v_rcp_f32_e32 v77, v77
.LBB0_435:
	v_or_b32_e32 v84, 48, v159
	v_mov_b64_e32 v[82:83], s[42:43]
	v_mad_i64_i32 v[82:83], s[2:3], v84, s7, v[82:83]
	v_lshl_add_u64 v[82:83], v[152:153], 1, v[82:83]
	s_and_b64 vcc, exec, s[40:41]
	v_cvt_pk_bf16_f32 v78, v78, v79
	v_cvt_pk_bf16_f32 v79, v80, v81
	v_cvt_pk_bf16_f32 v80, v74, v75
	v_cvt_pk_bf16_f32 v81, v76, v77
	ds_bpermute_b32 v222, v220, v82
	ds_bpermute_b32 v223, v220, v83
	ds_bpermute_b32 v78, v220, v78
	ds_bpermute_b32 v79, v220, v79
	ds_bpermute_b32 v80, v220, v80
	ds_bpermute_b32 v81, v220, v81
	s_waitcnt lgkmcnt(0)
	global_store_dwordx4 v[222:223], v[78:81], off sc1
	s_cbranch_vccnz .LBB0_437
	v_mul_f32_e32 v70, 0xbfb8aa3b, v70
	v_mul_f32_e32 v66, 0xbfb8aa3b, v66
	v_mul_f32_e32 v71, 0xbfb8aa3b, v71
	v_mul_f32_e32 v67, 0xbfb8aa3b, v67
	v_mul_f32_e32 v72, 0xbfb8aa3b, v72
	v_mul_f32_e32 v68, 0xbfb8aa3b, v68
	v_mul_f32_e32 v73, 0xbfb8aa3b, v73
	v_mul_f32_e32 v69, 0xbfb8aa3b, v69
	v_exp_f32_e32 v70, v70
	v_exp_f32_e32 v66, v66
	v_exp_f32_e32 v71, v71
	v_exp_f32_e32 v67, v67
	v_exp_f32_e32 v72, v72
	v_exp_f32_e32 v68, v68
	v_exp_f32_e32 v73, v73
	v_exp_f32_e32 v69, v69
	v_add_f32_e32 v70, 1.0, v70
	v_add_f32_e32 v66, 1.0, v66
	v_add_f32_e32 v71, 1.0, v71
	v_add_f32_e32 v67, 1.0, v67
	v_add_f32_e32 v72, 1.0, v72
	v_add_f32_e32 v68, 1.0, v68
	v_add_f32_e32 v73, 1.0, v73
	v_add_f32_e32 v69, 1.0, v69
	v_rcp_f32_e32 v70, v70
	v_rcp_f32_e32 v66, v66
	v_rcp_f32_e32 v71, v71
	v_rcp_f32_e32 v67, v67
	v_rcp_f32_e32 v72, v72
	v_rcp_f32_e32 v68, v68
	v_rcp_f32_e32 v73, v73
	v_rcp_f32_e32 v69, v69
; __device__ __forceinline__ unsigned cvt_pk_bf16(float lo, float hi) { unsigned r; asm volatile("v_cvt_pk_bf16_f32 %0, %1, %2" : "=v"(r) : "v"(lo), "v"(hi)); return r; }
; __device__ __forceinline__ float fsig(float x) { return __builtin_amdgcn_rcpf(1.0f + __expf(-x)); }
;     __device__ __forceinline__ void operator()(const f32x4 (&acc)[2][2][4][2], const Unit& u, int wr, int wc, int fr, int fq) const {
;         const int pn = u.pn;
;         const int act = (pn >= 33) ? 2 : 0;
;         const int row0 = u.pm * BM + wr * 64 + fr, col0 = pn * BM + wc * 32 + 8 * fq;
; #pragma unroll
;         for (int ai = 0; ai < 2; ++ai)
; #pragma unroll
;             for (int m = 0; m < 4; ++m) { bf16_t* rowp = O + (size_t)(row0 + ai * HALF + m * 16) * LDP + col0;
; #pragma unroll
;                 for (int bj = 0; bj < 2; ++bj) { f32x4 v0 = acc[ai][bj][m][0], v1 = acc[ai][bj][m][1];
;                     if (act == 1) {
; #pragma unroll
;                         for (int j = 0; j < 4; ++j) { v0[j] = v0[j] * fsig(v0[j]); v1[j] = v1[j] * fsig(v1[j]); } }
;                     else if (act == 2) {
; #pragma unroll
;                         for (int j = 0; j < 4; ++j) { v0[j] = fsig(v0[j]); v1[j] = fsig(v1[j]); } }
;                     u32x4 w; w.x = cvt_pk_bf16(v0[0], v0[1]); w.y = cvt_pk_bf16(v0[2], v0[3]); w.z = cvt_pk_bf16(v1[0], v1[1]); w.w = cvt_pk_bf16(v1[2], v1[3]);
;                     *(u32x4*)(rowp + bj * HALF) = w; } }
.LBB0_437:
	s_and_b64 vcc, exec, s[40:41]
	v_cvt_pk_bf16_f32 v70, v70, v71
	v_cvt_pk_bf16_f32 v71, v72, v73
	v_cvt_pk_bf16_f32 v72, v66, v67
	v_cvt_pk_bf16_f32 v73, v68, v69
	ds_bpermute_b32 v222, v220, v82
	ds_bpermute_b32 v223, v220, v83
	ds_bpermute_b32 v70, v220, v70
	ds_bpermute_b32 v71, v220, v71
	ds_bpermute_b32 v72, v220, v72
	ds_bpermute_b32 v73, v220, v73
	s_waitcnt lgkmcnt(0)
	global_store_dwordx4 v[222:223], v[70:73], off offset:256 sc1
	s_cbranch_vccnz .LBB0_439
	v_mul_f32_e32 v62, 0xbfb8aa3b, v62
	v_mul_f32_e32 v58, 0xbfb8aa3b, v58
	v_mul_f32_e32 v63, 0xbfb8aa3b, v63
	v_mul_f32_e32 v59, 0xbfb8aa3b, v59
	v_mul_f32_e32 v64, 0xbfb8aa3b, v64
	v_mul_f32_e32 v60, 0xbfb8aa3b, v60
	v_mul_f32_e32 v65, 0xbfb8aa3b, v65
	v_mul_f32_e32 v61, 0xbfb8aa3b, v61
	v_exp_f32_e32 v62, v62
	v_exp_f32_e32 v58, v58
	v_exp_f32_e32 v63, v63
	v_exp_f32_e32 v59, v59
	v_exp_f32_e32 v64, v64
	v_exp_f32_e32 v60, v60
	v_exp_f32_e32 v65, v65
	v_exp_f32_e32 v61, v61
	v_add_f32_e32 v62, 1.0, v62
	v_add_f32_e32 v58, 1.0, v58
	v_add_f32_e32 v63, 1.0, v63
	v_add_f32_e32 v59, 1.0, v59
	v_add_f32_e32 v64, 1.0, v64
	v_add_f32_e32 v60, 1.0, v60
	v_add_f32_e32 v65, 1.0, v65
	v_add_f32_e32 v61, 1.0, v61
	v_rcp_f32_e32 v62, v62
	v_rcp_f32_e32 v58, v58
	v_rcp_f32_e32 v63, v63
	v_rcp_f32_e32 v59, v59
	v_rcp_f32_e32 v64, v64
	v_rcp_f32_e32 v60, v60
	v_rcp_f32_e32 v65, v65
	v_rcp_f32_e32 v61, v61
.LBB0_439:
	v_add_u32_e32 v68, 0x80, v159
	v_mov_b64_e32 v[66:67], s[42:43]
	v_mad_i64_i32 v[66:67], s[2:3], v68, s7, v[66:67]
	v_lshl_add_u64 v[66:67], v[152:153], 1, v[66:67]
	s_and_b64 vcc, exec, s[40:41]
	v_cvt_pk_bf16_f32 v62, v62, v63
	v_cvt_pk_bf16_f32 v63, v64, v65
	v_cvt_pk_bf16_f32 v64, v58, v59
	v_cvt_pk_bf16_f32 v65, v60, v61
	ds_bpermute_b32 v222, v220, v66
	ds_bpermute_b32 v223, v220, v67
	ds_bpermute_b32 v62, v220, v62
	ds_bpermute_b32 v63, v220, v63
	ds_bpermute_b32 v64, v220, v64
	ds_bpermute_b32 v65, v220, v65
	s_waitcnt lgkmcnt(0)
	global_store_dwordx4 v[222:223], v[62:65], off sc1
	s_cbranch_vccnz .LBB0_441
	v_mul_f32_e32 v54, 0xbfb8aa3b, v54
	v_mul_f32_e32 v50, 0xbfb8aa3b, v50
	v_mul_f32_e32 v55, 0xbfb8aa3b, v55
	v_mul_f32_e32 v51, 0xbfb8aa3b, v51
	v_mul_f32_e32 v56, 0xbfb8aa3b, v56
	v_mul_f32_e32 v52, 0xbfb8aa3b, v52
	v_mul_f32_e32 v57, 0xbfb8aa3b, v57
	v_mul_f32_e32 v53, 0xbfb8aa3b, v53
	v_exp_f32_e32 v54, v54
	v_exp_f32_e32 v50, v50
	v_exp_f32_e32 v55, v55
	v_exp_f32_e32 v51, v51
	v_exp_f32_e32 v56, v56
	v_exp_f32_e32 v52, v52
	v_exp_f32_e32 v57, v57
	v_exp_f32_e32 v53, v53
	v_add_f32_e32 v54, 1.0, v54
	v_add_f32_e32 v50, 1.0, v50
	v_add_f32_e32 v55, 1.0, v55
	v_add_f32_e32 v51, 1.0, v51
	v_add_f32_e32 v56, 1.0, v56
	v_add_f32_e32 v52, 1.0, v52
	v_add_f32_e32 v57, 1.0, v57
	v_add_f32_e32 v53, 1.0, v53
	v_rcp_f32_e32 v54, v54
	v_rcp_f32_e32 v50, v50
	v_rcp_f32_e32 v55, v55
	v_rcp_f32_e32 v51, v51
	v_rcp_f32_e32 v56, v56
	v_rcp_f32_e32 v52, v52
	v_rcp_f32_e32 v57, v57
	v_rcp_f32_e32 v53, v53
.LBB0_441:
	s_and_b64 vcc, exec, s[40:41]
	v_cvt_pk_bf16_f32 v54, v54, v55
	v_cvt_pk_bf16_f32 v55, v56, v57
	v_cvt_pk_bf16_f32 v56, v50, v51
	v_cvt_pk_bf16_f32 v57, v52, v53
	ds_bpermute_b32 v222, v220, v66
	ds_bpermute_b32 v223, v220, v67
	ds_bpermute_b32 v54, v220, v54
	ds_bpermute_b32 v55, v220, v55
	ds_bpermute_b32 v56, v220, v56
	ds_bpermute_b32 v57, v220, v57
	s_waitcnt lgkmcnt(0)
	global_store_dwordx4 v[222:223], v[54:57], off offset:256 sc1
	s_cbranch_vccnz .LBB0_443
	v_mul_f32_e32 v46, 0xbfb8aa3b, v46
	v_mul_f32_e32 v42, 0xbfb8aa3b, v42
	v_mul_f32_e32 v47, 0xbfb8aa3b, v47
	v_mul_f32_e32 v43, 0xbfb8aa3b, v43
	v_mul_f32_e32 v48, 0xbfb8aa3b, v48
	v_mul_f32_e32 v44, 0xbfb8aa3b, v44
	v_mul_f32_e32 v49, 0xbfb8aa3b, v49
	v_mul_f32_e32 v45, 0xbfb8aa3b, v45
	v_exp_f32_e32 v46, v46
	v_exp_f32_e32 v42, v42
	v_exp_f32_e32 v47, v47
	v_exp_f32_e32 v43, v43
	v_exp_f32_e32 v48, v48
	v_exp_f32_e32 v44, v44
	v_exp_f32_e32 v49, v49
	v_exp_f32_e32 v45, v45
	v_add_f32_e32 v46, 1.0, v46
	v_add_f32_e32 v42, 1.0, v42
	v_add_f32_e32 v47, 1.0, v47
	v_add_f32_e32 v43, 1.0, v43
	v_add_f32_e32 v48, 1.0, v48
	v_add_f32_e32 v44, 1.0, v44
	v_add_f32_e32 v49, 1.0, v49
	v_add_f32_e32 v45, 1.0, v45
	v_rcp_f32_e32 v46, v46
	v_rcp_f32_e32 v42, v42
	v_rcp_f32_e32 v47, v47
	v_rcp_f32_e32 v43, v43
	v_rcp_f32_e32 v48, v48
	v_rcp_f32_e32 v44, v44
	v_rcp_f32_e32 v49, v49
	v_rcp_f32_e32 v45, v45
.LBB0_443:
	v_add_u32_e32 v52, 0x90, v159
	v_mov_b64_e32 v[50:51], s[42:43]
	v_mad_i64_i32 v[50:51], s[2:3], v52, s7, v[50:51]
	v_lshl_add_u64 v[50:51], v[152:153], 1, v[50:51]
	s_and_b64 vcc, exec, s[40:41]
	v_cvt_pk_bf16_f32 v46, v46, v47
	v_cvt_pk_bf16_f32 v47, v48, v49
	v_cvt_pk_bf16_f32 v48, v42, v43
	v_cvt_pk_bf16_f32 v49, v44, v45
	ds_bpermute_b32 v222, v220, v50
	ds_bpermute_b32 v223, v220, v51
	ds_bpermute_b32 v46, v220, v46
	ds_bpermute_b32 v47, v220, v47
	ds_bpermute_b32 v48, v220, v48
	ds_bpermute_b32 v49, v220, v49
	s_waitcnt lgkmcnt(0)
	global_store_dwordx4 v[222:223], v[46:49], off sc1
	s_cbranch_vccnz .LBB0_445
	v_mul_f32_e32 v38, 0xbfb8aa3b, v38
	v_mul_f32_e32 v34, 0xbfb8aa3b, v34
	v_mul_f32_e32 v39, 0xbfb8aa3b, v39
	v_mul_f32_e32 v35, 0xbfb8aa3b, v35
	v_mul_f32_e32 v40, 0xbfb8aa3b, v40
	v_mul_f32_e32 v36, 0xbfb8aa3b, v36
	v_mul_f32_e32 v41, 0xbfb8aa3b, v41
	v_mul_f32_e32 v37, 0xbfb8aa3b, v37
	v_exp_f32_e32 v38, v38
	v_exp_f32_e32 v34, v34
	v_exp_f32_e32 v39, v39
	v_exp_f32_e32 v35, v35
	v_exp_f32_e32 v40, v40
	v_exp_f32_e32 v36, v36
	v_exp_f32_e32 v41, v41
	v_exp_f32_e32 v37, v37
	v_add_f32_e32 v38, 1.0, v38
	v_add_f32_e32 v34, 1.0, v34
	v_add_f32_e32 v39, 1.0, v39
	v_add_f32_e32 v35, 1.0, v35
	v_add_f32_e32 v40, 1.0, v40
	v_add_f32_e32 v36, 1.0, v36
	v_add_f32_e32 v41, 1.0, v41
	v_add_f32_e32 v37, 1.0, v37
	v_rcp_f32_e32 v38, v38
	v_rcp_f32_e32 v34, v34
	v_rcp_f32_e32 v39, v39
	v_rcp_f32_e32 v35, v35
	v_rcp_f32_e32 v40, v40
	v_rcp_f32_e32 v36, v36
	v_rcp_f32_e32 v41, v41
	v_rcp_f32_e32 v37, v37
; __device__ __forceinline__ unsigned cvt_pk_bf16(float lo, float hi) { unsigned r; asm volatile("v_cvt_pk_bf16_f32 %0, %1, %2" : "=v"(r) : "v"(lo), "v"(hi)); return r; }
; __device__ __forceinline__ float fsig(float x) { return __builtin_amdgcn_rcpf(1.0f + __expf(-x)); }
;     __device__ __forceinline__ void operator()(const f32x4 (&acc)[2][2][4][2], const Unit& u, int wr, int wc, int fr, int fq) const {
;         const int pn = u.pn;
;         const int act = (pn >= 33) ? 2 : 0;
;         const int row0 = u.pm * BM + wr * 64 + fr, col0 = pn * BM + wc * 32 + 8 * fq;
; #pragma unroll
;         for (int ai = 0; ai < 2; ++ai)
; #pragma unroll
;             for (int m = 0; m < 4; ++m) { bf16_t* rowp = O + (size_t)(row0 + ai * HALF + m * 16) * LDP + col0;
; #pragma unroll
;                 for (int bj = 0; bj < 2; ++bj) { f32x4 v0 = acc[ai][bj][m][0], v1 = acc[ai][bj][m][1];
;                     if (act == 1) {
; #pragma unroll
;                         for (int j = 0; j < 4; ++j) { v0[j] = v0[j] * fsig(v0[j]); v1[j] = v1[j] * fsig(v1[j]); } }
;                     else if (act == 2) {
; #pragma unroll
;                         for (int j = 0; j < 4; ++j) { v0[j] = fsig(v0[j]); v1[j] = fsig(v1[j]); } }
;                     u32x4 w; w.x = cvt_pk_bf16(v0[0], v0[1]); w.y = cvt_pk_bf16(v0[2], v0[3]); w.z = cvt_pk_bf16(v1[0], v1[1]); w.w = cvt_pk_bf16(v1[2], v1[3]);
;                     *(u32x4*)(rowp + bj * HALF) = w; } }
; template <class Epi, class Sched, bool ALIGN_EPI = false, bool SP2 = false>
; __device__ __forceinline__ void gemm_phase(PG8_LAS unsigned char* lds, const Gemm g, const Sched& S, const Epi& E) {
;     ...
;         if constexpr (!Epi::AFTER_DRAIN) { E(acc, cur, wr, wc, fr, fq); S.done(cur); }
;         if (!has_next) break;
.LBB0_445:
	s_and_b64 vcc, exec, s[40:41]
	v_cvt_pk_bf16_f32 v38, v38, v39
	v_cvt_pk_bf16_f32 v39, v40, v41
	v_cvt_pk_bf16_f32 v40, v34, v35
	v_cvt_pk_bf16_f32 v41, v36, v37
	ds_bpermute_b32 v222, v220, v50
	ds_bpermute_b32 v223, v220, v51
	ds_bpermute_b32 v38, v220, v38
	ds_bpermute_b32 v39, v220, v39
	ds_bpermute_b32 v40, v220, v40
	ds_bpermute_b32 v41, v220, v41
	s_waitcnt lgkmcnt(0)
	global_store_dwordx4 v[222:223], v[38:41], off offset:256 sc1
	s_cbranch_vccnz .LBB0_447
	v_mul_f32_e32 v30, 0xbfb8aa3b, v30
	v_mul_f32_e32 v26, 0xbfb8aa3b, v26
	v_mul_f32_e32 v31, 0xbfb8aa3b, v31
	v_mul_f32_e32 v27, 0xbfb8aa3b, v27
	v_mul_f32_e32 v32, 0xbfb8aa3b, v32
	v_mul_f32_e32 v28, 0xbfb8aa3b, v28
	v_mul_f32_e32 v33, 0xbfb8aa3b, v33
	v_mul_f32_e32 v29, 0xbfb8aa3b, v29
	v_exp_f32_e32 v30, v30
	v_exp_f32_e32 v26, v26
	v_exp_f32_e32 v31, v31
	v_exp_f32_e32 v27, v27
	v_exp_f32_e32 v32, v32
	v_exp_f32_e32 v28, v28
	v_exp_f32_e32 v33, v33
	v_exp_f32_e32 v29, v29
	v_add_f32_e32 v30, 1.0, v30
	v_add_f32_e32 v26, 1.0, v26
	v_add_f32_e32 v31, 1.0, v31
	v_add_f32_e32 v27, 1.0, v27
	v_add_f32_e32 v32, 1.0, v32
	v_add_f32_e32 v28, 1.0, v28
	v_add_f32_e32 v33, 1.0, v33
	v_add_f32_e32 v29, 1.0, v29
	v_rcp_f32_e32 v30, v30
	v_rcp_f32_e32 v26, v26
	v_rcp_f32_e32 v31, v31
	v_rcp_f32_e32 v27, v27
	v_rcp_f32_e32 v32, v32
	v_rcp_f32_e32 v28, v28
	v_rcp_f32_e32 v33, v33
	v_rcp_f32_e32 v29, v29
.LBB0_447:
	v_add_u32_e32 v36, 0xa0, v159
	v_mov_b64_e32 v[34:35], s[42:43]
	v_mad_i64_i32 v[34:35], s[2:3], v36, s7, v[34:35]
	v_lshl_add_u64 v[34:35], v[152:153], 1, v[34:35]
	s_and_b64 vcc, exec, s[40:41]
	v_cvt_pk_bf16_f32 v30, v30, v31
	v_cvt_pk_bf16_f32 v31, v32, v33
	v_cvt_pk_bf16_f32 v32, v26, v27
	v_cvt_pk_bf16_f32 v33, v28, v29
	ds_bpermute_b32 v222, v220, v34
	ds_bpermute_b32 v223, v220, v35
	ds_bpermute_b32 v30, v220, v30
	ds_bpermute_b32 v31, v220, v31
	ds_bpermute_b32 v32, v220, v32
	ds_bpermute_b32 v33, v220, v33
	s_waitcnt lgkmcnt(0)
	global_store_dwordx4 v[222:223], v[30:33], off sc1
	s_cbranch_vccnz .LBB0_449
	v_mul_f32_e32 v22, 0xbfb8aa3b, v22
	v_mul_f32_e32 v18, 0xbfb8aa3b, v18
	v_mul_f32_e32 v23, 0xbfb8aa3b, v23
	v_mul_f32_e32 v19, 0xbfb8aa3b, v19
	v_mul_f32_e32 v24, 0xbfb8aa3b, v24
	v_mul_f32_e32 v20, 0xbfb8aa3b, v20
	v_mul_f32_e32 v25, 0xbfb8aa3b, v25
	v_mul_f32_e32 v21, 0xbfb8aa3b, v21
	v_exp_f32_e32 v22, v22
	v_exp_f32_e32 v18, v18
	v_exp_f32_e32 v23, v23
	v_exp_f32_e32 v19, v19
	v_exp_f32_e32 v24, v24
	v_exp_f32_e32 v20, v20
	v_exp_f32_e32 v25, v25
	v_exp_f32_e32 v21, v21
	v_add_f32_e32 v22, 1.0, v22
	v_add_f32_e32 v18, 1.0, v18
	v_add_f32_e32 v23, 1.0, v23
	v_add_f32_e32 v19, 1.0, v19
	v_add_f32_e32 v24, 1.0, v24
	v_add_f32_e32 v20, 1.0, v20
	v_add_f32_e32 v25, 1.0, v25
	v_add_f32_e32 v21, 1.0, v21
	v_rcp_f32_e32 v22, v22
	v_rcp_f32_e32 v18, v18
	v_rcp_f32_e32 v23, v23
	v_rcp_f32_e32 v19, v19
	v_rcp_f32_e32 v24, v24
	v_rcp_f32_e32 v20, v20
	v_rcp_f32_e32 v25, v25
	v_rcp_f32_e32 v21, v21
.LBB0_449:
	s_and_b64 vcc, exec, s[40:41]
	v_cvt_pk_bf16_f32 v22, v22, v23
	v_cvt_pk_bf16_f32 v23, v24, v25
	v_cvt_pk_bf16_f32 v24, v18, v19
	v_cvt_pk_bf16_f32 v25, v20, v21
	ds_bpermute_b32 v222, v220, v34
	ds_bpermute_b32 v223, v220, v35
	ds_bpermute_b32 v22, v220, v22
	ds_bpermute_b32 v23, v220, v23
	ds_bpermute_b32 v24, v220, v24
	ds_bpermute_b32 v25, v220, v25
	s_waitcnt lgkmcnt(0)
	global_store_dwordx4 v[222:223], v[22:25], off offset:256 sc1
	s_cbranch_vccnz .LBB0_451
	v_mul_f32_e32 v14, 0xbfb8aa3b, v14
	v_mul_f32_e32 v10, 0xbfb8aa3b, v10
	v_mul_f32_e32 v15, 0xbfb8aa3b, v15
	v_mul_f32_e32 v11, 0xbfb8aa3b, v11
	v_mul_f32_e32 v16, 0xbfb8aa3b, v16
	v_mul_f32_e32 v12, 0xbfb8aa3b, v12
	v_mul_f32_e32 v17, 0xbfb8aa3b, v17
	v_mul_f32_e32 v13, 0xbfb8aa3b, v13
	v_exp_f32_e32 v14, v14
	v_exp_f32_e32 v10, v10
	v_exp_f32_e32 v15, v15
	v_exp_f32_e32 v11, v11
	v_exp_f32_e32 v16, v16
	v_exp_f32_e32 v12, v12
	v_exp_f32_e32 v17, v17
	v_exp_f32_e32 v13, v13
	v_add_f32_e32 v14, 1.0, v14
	v_add_f32_e32 v10, 1.0, v10
	v_add_f32_e32 v15, 1.0, v15
	v_add_f32_e32 v11, 1.0, v11
	v_add_f32_e32 v16, 1.0, v16
	v_add_f32_e32 v12, 1.0, v12
	v_add_f32_e32 v17, 1.0, v17
	v_add_f32_e32 v13, 1.0, v13
	v_rcp_f32_e32 v14, v14
	v_rcp_f32_e32 v10, v10
	v_rcp_f32_e32 v15, v15
	v_rcp_f32_e32 v11, v11
	v_rcp_f32_e32 v16, v16
	v_rcp_f32_e32 v12, v12
	v_rcp_f32_e32 v17, v17
	v_rcp_f32_e32 v13, v13
.LBB0_451:
	v_add_u32_e32 v20, 0xb0, v159
	v_mov_b64_e32 v[18:19], s[42:43]
	v_mad_i64_i32 v[18:19], s[2:3], v20, s7, v[18:19]
	v_lshl_add_u64 v[18:19], v[152:153], 1, v[18:19]
	s_and_b64 vcc, exec, s[40:41]
	v_cvt_pk_bf16_f32 v14, v14, v15
	v_cvt_pk_bf16_f32 v15, v16, v17
	v_cvt_pk_bf16_f32 v16, v10, v11
	v_cvt_pk_bf16_f32 v17, v12, v13
	ds_bpermute_b32 v222, v220, v18
	ds_bpermute_b32 v223, v220, v19
	ds_bpermute_b32 v14, v220, v14
	ds_bpermute_b32 v15, v220, v15
	ds_bpermute_b32 v16, v220, v16
	ds_bpermute_b32 v17, v220, v17
	s_waitcnt lgkmcnt(0)
	global_store_dwordx4 v[222:223], v[14:17], off sc1
	s_cbranch_vccnz .LBB0_453
	v_mul_f32_e32 v6, 0xbfb8aa3b, v6
	v_mul_f32_e32 v2, 0xbfb8aa3b, v2
	v_mul_f32_e32 v7, 0xbfb8aa3b, v7
	v_mul_f32_e32 v3, 0xbfb8aa3b, v3
	v_mul_f32_e32 v8, 0xbfb8aa3b, v8
	v_mul_f32_e32 v4, 0xbfb8aa3b, v4
	v_mul_f32_e32 v9, 0xbfb8aa3b, v9
	v_mul_f32_e32 v5, 0xbfb8aa3b, v5
	v_exp_f32_e32 v6, v6
	v_exp_f32_e32 v2, v2
	v_exp_f32_e32 v7, v7
	v_exp_f32_e32 v3, v3
	v_exp_f32_e32 v8, v8
	v_exp_f32_e32 v4, v4
	v_exp_f32_e32 v9, v9
	v_exp_f32_e32 v5, v5
	v_add_f32_e32 v6, 1.0, v6
	v_add_f32_e32 v2, 1.0, v2
	v_add_f32_e32 v7, 1.0, v7
	v_add_f32_e32 v3, 1.0, v3
	v_add_f32_e32 v8, 1.0, v8
	v_add_f32_e32 v4, 1.0, v4
	v_add_f32_e32 v9, 1.0, v9
	v_add_f32_e32 v5, 1.0, v5
	v_rcp_f32_e32 v6, v6
	v_rcp_f32_e32 v2, v2
	v_rcp_f32_e32 v7, v7
	v_rcp_f32_e32 v3, v3
	v_rcp_f32_e32 v8, v8
	v_rcp_f32_e32 v4, v4
	v_rcp_f32_e32 v9, v9
	v_rcp_f32_e32 v5, v5
.LBB0_453:
	s_andn2_b64 vcc, exec, s[38:39]
	s_mov_b64 s[2:3], -1
	v_cvt_pk_bf16_f32 v6, v6, v7
	v_cvt_pk_bf16_f32 v7, v8, v9
	v_cvt_pk_bf16_f32 v8, v2, v3
	v_cvt_pk_bf16_f32 v9, v4, v5
	ds_bpermute_b32 v222, v220, v18
	ds_bpermute_b32 v223, v220, v19
	ds_bpermute_b32 v6, v220, v6
	ds_bpermute_b32 v7, v220, v7
	ds_bpermute_b32 v8, v220, v8
	ds_bpermute_b32 v9, v220, v9
	s_waitcnt lgkmcnt(0)
	global_store_dwordx4 v[222:223], v[6:9], off offset:256 sc1
	s_cbranch_vccnz .LBB0_414
	s_andn2_b64 vcc, exec, s[0:1]
	s_cbranch_vccnz .LBB0_413
	s_barrier
	s_branch .LBB0_413
